# P0 x->bf16 loop unrolled x5 (10 loads in flight per lane)
# baseline (speedup 1.0000x reference)
; #define GAS __attribute__((address_space(1)))
; __device__ __forceinline__ unsigned pk2(float lo, float hi) { const f32x2 v = {lo, hi}; const bf16x2_t b = __builtin_convertvector(v, bf16x2_t); return __builtin_bit_cast(unsigned, b); }
; __device__ __forceinline__ void p0_prologue(Frame& F) {
;     ...
;     { const size_t nth = (size_t)F.NGW * 64, t0 = (size_t)F.gw * 64 + lane; const size_t NP8 = (size_t)MP * D / 8, NT8 = (size_t)M * D / 8;
;       for (size_t i = t0; i < NT8; i += nth) { const float* s = i < NP8 ? F.a->in[I_XP] + i * 8 : F.a->in[I_XS] + (i - NP8) * 8; const f32x4 a = *(const GAS f32x4*)s, b = *(const GAS f32x4*)(s + 4);
;           v4u o; o.x = pk2(a.x, a.y); o.y = pk2(a.z, a.w); o.z = pk2(b.x, b.y); o.w = pk2(b.z, b.w); *(GAS v4u*)(F.XB() + i * 8) = o; } }
.LBB0_112:
	v_readlane_b32 s0, v255, 31
	v_readlane_b32 s1, v255, 32
	s_ashr_i32 s1, s0, 31
	v_writelane_b32 v255, s0, 31
	v_ashrrev_i32_e32 v1, 31, v0
	s_nop 0
	v_writelane_b32 v255, s1, 32
	s_lshl_b64 s[0:1], s[0:1], 6
	v_lshl_add_u64 v[2:3], s[0:1], 0, v[0:1]
	s_mov_b64 s[0:1], 0x820000
	v_cmp_gt_u64_e32 vcc, s[0:1], v[2:3]
	s_and_saveexec_b64 s[0:1], vcc
	s_cbranch_execz .LBB0_115
	v_readlane_b32 s2, v255, 33
	v_readlane_b32 s3, v255, 34
	s_mov_b32 s10, s2
	s_ashr_i32 s11, s2, 31
	s_lshl_b64 s[2:3], s[10:11], 6
	v_readlane_b32 s8, v255, 31
	s_add_u32 s4, s54, 0xf0000000
	v_readlane_b32 s9, v255, 32
	s_addc_u32 s5, s55, -1
	s_lshl_b64 s[6:7], s[8:9], 11
	v_lshlrev_b64 v[4:5], 5, v[0:1]
	s_mov_b64 s[12:13], s[84:85]
	v_lshl_add_u64 v[4:5], s[6:7], 0, v[4:5]
	s_lshl_b64 s[6:7], s[10:11], 11
	s_lshl_b64 s[8:9], s[8:9], 10
	s_mov_b64 s[18:19], s[90:91]
	s_add_u32 s8, s18, s8
	s_addc_u32 s9, s19, s9
	v_lshl_add_u64 v[6:7], v[0:1], 4, s[8:9]
	s_mov_b64 s[8:9], 0x2000000
	v_lshl_add_u64 v[6:7], v[6:7], 0, s[8:9]
	s_mov_b32 s8, s10
	s_mov_b64 s[14:15], s[86:87]
	v_writelane_b32 v255, s8, 33
	s_mov_b64 s[12:13], 0x800000
	s_mov_b64 s[14:15], 0x81ffff
	v_writelane_b32 v255, s9, 34
	s_lshl_b64 s[8:9], s[10:11], 10
	s_mov_b64 s[10:11], 0
	s_mov_b64 s[16:17], s[88:89]
	s_lshl_b64 s[32:33], s[2:3], 2
.Lxcvt5_top:
	v_lshl_add_u64 v[150:151], s[32:33], 0, v[2:3]
	v_cmp_ge_u64_e32 vcc, s[14:15], v[150:151]
	s_xor_b64 s[34:35], vcc, exec
	s_cbranch_scc1 .Lxcvt5_rem
	v_lshl_add_u64 v[152:153], s[52:53], 0, v[4:5]
	v_lshl_add_u64 v[150:151], s[4:5], 0, v[4:5]
	v_cmp_gt_u64_e32 vcc, s[12:13], v[2:3]
	v_lshl_add_u64 v[202:203], v[2:3], 0, s[2:3]
	v_lshl_add_u64 v[204:205], v[4:5], 0, s[6:7]
	v_cndmask_b32_e32 v153, v151, v153, vcc
	v_cndmask_b32_e32 v152, v150, v152, vcc
	global_load_dwordx4 v[162:165], v[152:153], off
	global_load_dwordx4 v[166:169], v[152:153], off offset:16
	v_lshl_add_u64 v[154:155], s[52:53], 0, v[204:205]
	v_lshl_add_u64 v[150:151], s[4:5], 0, v[204:205]
	v_cmp_gt_u64_e32 vcc, s[12:13], v[202:203]
	v_lshl_add_u64 v[202:203], v[202:203], 0, s[2:3]
	v_lshl_add_u64 v[204:205], v[204:205], 0, s[6:7]
	v_cndmask_b32_e32 v155, v151, v155, vcc
	v_cndmask_b32_e32 v154, v150, v154, vcc
	global_load_dwordx4 v[170:173], v[154:155], off
	global_load_dwordx4 v[174:177], v[154:155], off offset:16
	v_lshl_add_u64 v[156:157], s[52:53], 0, v[204:205]
	v_lshl_add_u64 v[150:151], s[4:5], 0, v[204:205]
	v_cmp_gt_u64_e32 vcc, s[12:13], v[202:203]
	v_lshl_add_u64 v[202:203], v[202:203], 0, s[2:3]
	v_lshl_add_u64 v[204:205], v[204:205], 0, s[6:7]
	v_cndmask_b32_e32 v157, v151, v157, vcc
	v_cndmask_b32_e32 v156, v150, v156, vcc
	global_load_dwordx4 v[178:181], v[156:157], off
	global_load_dwordx4 v[182:185], v[156:157], off offset:16
	v_lshl_add_u64 v[158:159], s[52:53], 0, v[204:205]
	v_lshl_add_u64 v[150:151], s[4:5], 0, v[204:205]
	v_cmp_gt_u64_e32 vcc, s[12:13], v[202:203]
	v_lshl_add_u64 v[202:203], v[202:203], 0, s[2:3]
	v_lshl_add_u64 v[204:205], v[204:205], 0, s[6:7]
	v_cndmask_b32_e32 v159, v151, v159, vcc
	v_cndmask_b32_e32 v158, v150, v158, vcc
	global_load_dwordx4 v[186:189], v[158:159], off
	global_load_dwordx4 v[190:193], v[158:159], off offset:16
	v_lshl_add_u64 v[160:161], s[52:53], 0, v[204:205]
	v_lshl_add_u64 v[150:151], s[4:5], 0, v[204:205]
	v_cmp_gt_u64_e32 vcc, s[12:13], v[202:203]
	v_lshl_add_u64 v[2:3], v[202:203], 0, s[2:3]
	v_lshl_add_u64 v[4:5], v[204:205], 0, s[6:7]
	v_cndmask_b32_e32 v161, v151, v161, vcc
	v_cndmask_b32_e32 v160, v150, v160, vcc
	global_load_dwordx4 v[194:197], v[160:161], off
	global_load_dwordx4 v[198:201], v[160:161], off offset:16
	s_waitcnt vmcnt(8)
	v_cvt_pk_bf16_f32 v162, v162, v163
	v_cvt_pk_bf16_f32 v163, v164, v165
	v_cvt_pk_bf16_f32 v164, v166, v167
	v_cvt_pk_bf16_f32 v165, v168, v169
	global_store_dwordx4 v[6:7], v[162:165], off
	v_lshl_add_u64 v[6:7], v[6:7], 0, s[8:9]
	s_waitcnt vmcnt(7)
	v_cvt_pk_bf16_f32 v170, v170, v171
	v_cvt_pk_bf16_f32 v171, v172, v173
	v_cvt_pk_bf16_f32 v172, v174, v175
	v_cvt_pk_bf16_f32 v173, v176, v177
	global_store_dwordx4 v[6:7], v[170:173], off
	v_lshl_add_u64 v[6:7], v[6:7], 0, s[8:9]
	s_waitcnt vmcnt(6)
	v_cvt_pk_bf16_f32 v178, v178, v179
	v_cvt_pk_bf16_f32 v179, v180, v181
	v_cvt_pk_bf16_f32 v180, v182, v183
	v_cvt_pk_bf16_f32 v181, v184, v185
	global_store_dwordx4 v[6:7], v[178:181], off
	v_lshl_add_u64 v[6:7], v[6:7], 0, s[8:9]
	s_waitcnt vmcnt(5)
	v_cvt_pk_bf16_f32 v186, v186, v187
	v_cvt_pk_bf16_f32 v187, v188, v189
	v_cvt_pk_bf16_f32 v188, v190, v191
	v_cvt_pk_bf16_f32 v189, v192, v193
	global_store_dwordx4 v[6:7], v[186:189], off
	v_lshl_add_u64 v[6:7], v[6:7], 0, s[8:9]
	s_waitcnt vmcnt(4)
	v_cvt_pk_bf16_f32 v194, v194, v195
	v_cvt_pk_bf16_f32 v195, v196, v197
	v_cvt_pk_bf16_f32 v196, v198, v199
	v_cvt_pk_bf16_f32 v197, v200, v201
	global_store_dwordx4 v[6:7], v[194:197], off
	v_lshl_add_u64 v[6:7], v[6:7], 0, s[8:9]
	s_branch .Lxcvt5_top
.Lxcvt5_rem:
	v_cmp_ge_u64_e32 vcc, s[14:15], v[2:3]
	s_and_b64 exec, exec, vcc
	s_cbranch_execz .LBB0_115
